# stack: coalesced attention epilogue via LDS transpose + retA two-deep q/k prefetch on top of v114
# speedup vs baseline: 1.0071x; 1.0071x over previous
.LBB0_345:
	s_setprio 0
	v_readlane_b32 s0, v255, 1
	s_barrier
	v_mbcnt_lo_u32_b32 v33, -1, 0
	v_mbcnt_hi_u32_b32 v33, -1, v33
	s_cmpk_gt_u32 s2, 0x7ff
	v_add_u32_e32 v0, s0, v33
	v_ashrrev_i32_e32 v32, 5, v0
	v_and_b32_e32 v34, 31, v33
	s_cbranch_scc1 .LBB0_347
	s_lshl_b32 s0, s2, 4
	s_lshl_b32 s1, s2, 6
	s_and_b32 s0, s0, 0x6000
	s_and_b32 s1, s1, 0x1fc0
	s_or_b32 s0, s0, s1
	v_add_u32_e32 v2, s0, v32
	s_movk_i32 s0, 0x3000
	v_mov_b64_e32 v[0:1], s[62:63]
	v_mad_i64_i32 v[0:1], s[0:1], v2, s0, v[0:1]
	s_lshl_b32 s0, s2, 2
	s_and_b32 s0, s0, 0x600
	s_mov_b32 s1, 0
	v_lshl_add_u64 v[0:1], v[0:1], 0, s[0:1]
	v_lshlrev_b32_e32 v2, 4, v34
	v_mov_b32_e32 v3, 0
	v_lshl_add_u64 v[20:21], v[0:1], 0, v[2:3]
	s_mov_b32 s0, 0x30000
	v_add_co_u32_e32 v12, vcc, s0, v20
	s_mov_b32 s0, 0x60000
	s_nop 0
	v_addc_co_u32_e32 v13, vcc, 0, v21, vcc
	v_add_co_u32_e32 v22, vcc, s0, v20
	s_mov_b32 s0, 0x90000
	s_nop 0
	v_addc_co_u32_e32 v23, vcc, 0, v21, vcc
	v_add_co_u32_e32 v36, vcc, s0, v20
	global_load_dwordx4 v[144:147], v[20:21], off
	global_load_dwordx4 v[148:151], v[20:21], off offset:2048
	v_addc_co_u32_e32 v37, vcc, 0, v21, vcc
	global_load_dwordx4 v[152:155], v[12:13], off
	global_load_dwordx4 v[156:159], v[12:13], off offset:2048
	global_load_dwordx4 v[160:163], v[22:23], off
	s_nop 0
	global_load_dwordx4 v[164:167], v[22:23], off offset:2048
	global_load_dwordx4 v[168:171], v[36:37], off
	s_nop 0
	global_load_dwordx4 v[172:175], v[36:37], off offset:2048
	s_add_i32 s4, s2, s33
	s_cmpk_lt_i32 s4, 0x800
	s_cselect_b32 s4, s4, s2
	s_lshl_b32 s0, s4, 4
	s_lshl_b32 s1, s4, 6
	s_and_b32 s0, s0, 0x6000
	s_and_b32 s1, s1, 0x1fc0
	s_or_b32 s0, s0, s1
	v_add_u32_e32 v2, s0, v32
	s_movk_i32 s0, 0x3000
	v_mov_b64_e32 v[0:1], s[62:63]
	v_mad_i64_i32 v[0:1], s[0:1], v2, s0, v[0:1]
	s_lshl_b32 s0, s4, 2
	s_and_b32 s0, s0, 0x600
	s_mov_b32 s1, 0
	v_lshl_add_u64 v[0:1], v[0:1], 0, s[0:1]
	v_lshlrev_b32_e32 v2, 4, v34
	v_mov_b32_e32 v3, 0
	v_lshl_add_u64 v[20:21], v[0:1], 0, v[2:3]
	s_mov_b32 s0, 0x30000
	v_add_co_u32_e32 v12, vcc, s0, v20
	s_mov_b32 s0, 0x60000
	s_nop 0
	v_addc_co_u32_e32 v13, vcc, 0, v21, vcc
	v_add_co_u32_e32 v22, vcc, s0, v20
	s_mov_b32 s0, 0x90000
	s_nop 0
	v_addc_co_u32_e32 v23, vcc, 0, v21, vcc
	v_add_co_u32_e32 v36, vcc, s0, v20
	global_load_dwordx4 v[176:179], v[20:21], off
	global_load_dwordx4 v[180:183], v[20:21], off offset:2048
	v_addc_co_u32_e32 v37, vcc, 0, v21, vcc
	global_load_dwordx4 v[184:187], v[12:13], off
	global_load_dwordx4 v[188:191], v[12:13], off offset:2048
	global_load_dwordx4 v[192:195], v[22:23], off
	s_nop 0
	global_load_dwordx4 v[196:199], v[22:23], off offset:2048
	global_load_dwordx4 v[200:203], v[36:37], off
	s_nop 0
	global_load_dwordx4 v[204:207], v[36:37], off offset:2048
	s_waitcnt vmcnt(8)
	s_branch .LBB0_348

.LBB0_350:
	s_bfe_u32 s4, s36, 0x20007
	s_waitcnt vmcnt(10)
	ds_write_b128 v46, v[144:147]
	ds_write_b128 v46, v[148:151] offset:33792
	ds_write_b128 v46, v[152:155] offset:8448
	ds_write_b128 v46, v[156:159] offset:42240
	ds_write_b128 v46, v[160:163] offset:16896
	ds_write_b128 v46, v[164:167] offset:50688
	ds_write_b128 v46, v[168:171] offset:25344
	ds_write_b128 v46, v[172:175] offset:59136
	v_cvt_f32_ubyte0_e32 v26, s4
	v_sub_f32_e32 v26, 0xc0a00000, v26
	v_cmp_gt_f32_e32 vcc, s0, v26
	s_and_b64 s[4:5], vcc, exec
	s_cselect_b32 s6, 0xffffffc0, 0
	s_add_i32 s10, s36, s33
	v_cndmask_b32_e32 v27, 0, v50, vcc
	s_cmpk_lt_i32 s10, 0x800
	v_add_f32_e32 v26, v26, v27
	s_cselect_b64 s[4:5], -1, 0
	v_exp_f32_e32 v26, v26
	s_and_b64 vcc, s[4:5], exec
	s_waitcnt lgkmcnt(0)
	s_barrier
	ds_read_b128 v[0:3], v47
	ds_read_b128 v[4:7], v47 offset:64
	ds_read_b128 v[8:11], v48 offset:33792
	ds_read_b128 v[12:15], v48 offset:33856
	ds_read_b128 v[16:19], v49 offset:33792
	ds_read_b128 v[20:23], v49 offset:33856
	ds_read_b128 v[52:55], v47 offset:128
	ds_read_b128 v[56:59], v47 offset:192
	ds_read_b128 v[60:63], v48 offset:33920
	ds_read_b128 v[64:67], v48 offset:33984
	ds_read_b128 v[68:71], v49 offset:33920
	ds_read_b128 v[72:75], v49 offset:33984
	ds_read_b128 v[76:79], v47 offset:256
	ds_read_b128 v[80:83], v47 offset:320
	ds_read_b128 v[84:87], v48 offset:34048
	ds_read_b128 v[88:91], v48 offset:34112
	ds_read_b128 v[92:95], v49 offset:34048
	ds_read_b128 v[96:99], v49 offset:34112
	ds_read_b128 v[100:103], v47 offset:384
	ds_read_b128 v[104:107], v47 offset:448
	ds_read_b128 v[108:111], v48 offset:34176
	ds_read_b128 v[112:115], v48 offset:34240
	ds_read_b128 v[116:119], v49 offset:34176
	ds_read_b128 v[120:123], v49 offset:34240
	s_add_i32 s5, s10, s33
	s_cmpk_lt_i32 s5, 0x800
	s_cselect_b32 s5, s5, s36
	s_waitcnt lgkmcnt(14)
	v_mfma_f32_16x16x32_bf16 v[8:11], v[8:11], v[0:3], 0
	s_ashr_i32 s4, s5, 9
	s_ashr_i32 s37, s36, 31
	s_lshl_b32 s11, s5, 6
	v_mfma_f32_16x16x32_bf16 v[0:3], v[16:19], v[0:3], 0
	s_lshl_b32 s12, s5, 2
	s_ashr_i32 s5, s4, 31
	v_ldexp_f32 v26, v26, s6
	s_lshl_b64 s[6:7], s[36:37], 13
	s_mov_b32 s36, s10
	s_and_b32 s10, s11, 0x1fc0
	s_lshl_b64 s[4:5], s[4:5], 13
	s_or_b32 s4, s4, s10
	v_mov_b64_e32 v[24:25], s[62:63]
	v_mfma_f32_16x16x32_bf16 v[128:131], v[20:23], v[4:7], v[0:3]
	s_and_b32 s24, s12, 0x600
	v_sub_f32_e32 v16, 1.0, v26
	v_log_f32_e32 v134, v16
	v_lshl_add_u64 v[0:1], s[4:5], 0, v[32:33]
	v_mad_u64_u32 v[2:3], s[4:5], v0, s1, v[24:25]
	v_mad_i32_i24 v3, v1, s1, v3
	v_lshl_add_u64 v[0:1], v[2:3], 0, s[24:25]
	v_mfma_f32_16x16x32_bf16 v[124:127], v[12:15], v[4:7], v[8:11]
	v_mul_f32_e32 v135, v134, v39
	v_mul_f32_e32 v136, v134, v40
	v_mul_f32_e32 v137, v134, v41
	v_lshl_add_u64 v[8:9], v[0:1], 0, v[34:35]
	v_add_co_u32_e64 v10, s[4:5], s27, v8
	global_load_dwordx4 v[144:147], v[8:9], off
	global_load_dwordx4 v[148:151], v[8:9], off offset:2048
	v_addc_co_u32_e64 v11, s[4:5], 0, v9, s[4:5]
	v_add_co_u32_e64 v12, s[4:5], s38, v8
	v_mfma_f32_16x16x32_bf16 v[60:63], v[60:63], v[52:55], v[124:127]
	s_nop 0
	v_addc_co_u32_e64 v13, s[4:5], 0, v9, s[4:5]
	v_add_co_u32_e64 v20, s[4:5], s39, v8
	s_waitcnt lgkmcnt(13)
	v_mfma_f32_16x16x32_bf16 v[52:55], v[68:71], v[52:55], v[128:131]
	v_addc_co_u32_e64 v21, s[4:5], 0, v9, s[4:5]
	global_load_dwordx4 v[152:155], v[10:11], off
	s_nop 0
	global_load_dwordx4 v[156:159], v[10:11], off offset:2048
	s_nop 0
	global_load_dwordx4 v[160:163], v[12:13], off
	s_nop 0
	global_load_dwordx4 v[164:167], v[12:13], off offset:2048
	s_nop 0
	global_load_dwordx4 v[168:171], v[20:21], off
	s_nop 0
	global_load_dwordx4 v[172:175], v[20:21], off offset:2048
	v_mfma_f32_16x16x32_bf16 v[60:63], v[64:67], v[56:59], v[60:63]
	v_mul_f32_e32 v138, v134, v42
	v_lshl_add_u64 v[132:133], v[36:37], 0, s[6:7]
	v_mul_f32_e32 v139, v134, v38
	s_waitcnt lgkmcnt(12)
	v_mfma_f32_16x16x32_bf16 v[52:55], v[72:75], v[56:59], v[52:55]
	v_mul_f32_e32 v140, v134, v43
	v_mul_f32_e32 v141, v134, v44
	v_mul_f32_e32 v142, v134, v45
	s_waitcnt lgkmcnt(9)
	v_mfma_f32_16x16x32_bf16 v[56:59], v[84:87], v[76:79], v[60:63]
	v_cmp_gt_f32_e64 s[4:5], s0, v135
	v_cmp_gt_f32_e64 s[6:7], s0, v136
	v_cmp_gt_f32_e64 s[10:11], s0, v137
	s_waitcnt lgkmcnt(7)
	v_mfma_f32_16x16x32_bf16 v[52:55], v[92:95], v[76:79], v[52:55]
	v_cmp_gt_f32_e64 s[12:13], s0, v138
	v_cndmask_b32_e64 v135, 0, v50, s[4:5]
	v_cndmask_b32_e64 v136, 0, v50, s[6:7]
	v_mfma_f32_16x16x32_bf16 v[56:59], v[88:91], v[80:83], v[56:59]
	v_cndmask_b32_e64 v137, 0, v50, s[10:11]
	v_cndmask_b32_e64 v138, 0, v50, s[12:13]
	v_cmp_gt_f32_e64 s[14:15], s0, v139
	s_waitcnt lgkmcnt(6)
	v_mfma_f32_16x16x32_bf16 v[52:55], v[96:99], v[80:83], v[52:55]
	v_cmp_gt_f32_e64 s[16:17], s0, v140
	v_cmp_gt_f32_e64 s[18:19], s0, v141
	v_cmp_gt_f32_e64 s[20:21], s0, v142
	s_waitcnt lgkmcnt(3)
	v_mfma_f32_16x16x32_bf16 v[56:59], v[108:111], v[100:103], v[56:59]
	v_cndmask_b32_e64 v139, 0, v50, s[14:15]
	v_cndmask_b32_e64 v140, 0, v50, s[16:17]
	v_cndmask_b32_e64 v124, 0, v50, s[18:19]
	s_waitcnt lgkmcnt(1)
	v_mfma_f32_16x16x32_bf16 v[52:55], v[116:119], v[100:103], v[52:55]
	v_cndmask_b32_e64 v125, 0, v50, s[20:21]
	v_fmac_f32_e32 v135, v134, v39
	v_fmac_f32_e32 v136, v134, v40
	v_fmac_f32_e32 v137, v134, v41
	v_fmac_f32_e32 v138, v134, v42
	v_fmac_f32_e32 v139, v134, v38
	v_fmac_f32_e32 v140, v134, v43
	v_fmac_f32_e32 v124, v134, v44
	v_fmac_f32_e32 v125, v134, v45
	v_exp_f32_e32 v60, v135
	v_exp_f32_e32 v61, v136
	v_exp_f32_e32 v62, v137
	v_exp_f32_e32 v63, v138
	v_exp_f32_e32 v72, v139
	v_exp_f32_e32 v73, v140
	v_exp_f32_e32 v74, v124
	v_exp_f32_e32 v75, v125
	v_mfma_f32_16x16x32_bf16 v[56:59], v[112:115], v[104:107], v[56:59]
	v_cndmask_b32_e64 v68, 0, v51, s[4:5]
	v_cndmask_b32_e64 v69, 0, v51, s[6:7]
	v_cndmask_b32_e64 v64, 0, v51, s[10:11]
	s_waitcnt lgkmcnt(0)
	v_mfma_f32_16x16x32_bf16 v[52:55], v[120:123], v[104:107], v[52:55]
	v_cndmask_b32_e64 v65, 0, v51, s[12:13]
	v_cndmask_b32_e64 v66, 0, v51, s[14:15]
	v_cndmask_b32_e64 v67, 0, v51, s[16:17]
	v_cndmask_b32_e64 v70, 0, v51, s[18:19]
	v_cndmask_b32_e64 v71, 0, v51, s[20:21]
	v_ldexp_f32 v60, v60, v68
	v_ldexp_f32 v61, v61, v69
	v_ldexp_f32 v62, v62, v64
	v_ldexp_f32 v63, v63, v65
	v_ldexp_f32 v64, v72, v66
	v_ldexp_f32 v65, v73, v67
	v_ldexp_f32 v66, v74, v70
	v_ldexp_f32 v67, v75, v71
	v_pk_mul_f32 v[56:57], v[60:61], v[56:57]
	v_pk_mul_f32 v[58:59], v[62:63], v[58:59]
	v_pk_mul_f32 v[52:53], v[64:65], v[52:53]
	v_pk_mul_f32 v[54:55], v[66:67], v[54:55]
	v_cvt_pk_bf16_f32 v56, v56, v57
	v_cvt_pk_bf16_f32 v57, v58, v59
	v_cvt_pk_bf16_f32 v52, v52, v53
	v_cvt_pk_bf16_f32 v53, v54, v55
	global_store_dwordx2 v[132:133], v[56:57], off
	global_store_dwordx2 v[132:133], v[52:53], off offset:32
	s_barrier
	s_cbranch_vccz .LBB0_351
	s_bfe_u32 s4, s36, 0x20007
	s_waitcnt vmcnt(10)
	ds_write_b128 v46, v[176:179]
	ds_write_b128 v46, v[180:183] offset:33792
	ds_write_b128 v46, v[184:187] offset:8448
	ds_write_b128 v46, v[188:191] offset:42240
	ds_write_b128 v46, v[192:195] offset:16896
	ds_write_b128 v46, v[196:199] offset:50688
	ds_write_b128 v46, v[200:203] offset:25344
	ds_write_b128 v46, v[204:207] offset:59136
	v_cvt_f32_ubyte0_e32 v26, s4
	v_sub_f32_e32 v26, 0xc0a00000, v26
	v_cmp_gt_f32_e32 vcc, s0, v26
	s_and_b64 s[4:5], vcc, exec
	s_cselect_b32 s6, 0xffffffc0, 0
	s_add_i32 s10, s36, s33
	v_cndmask_b32_e32 v27, 0, v50, vcc
	s_cmpk_lt_i32 s10, 0x800
	v_add_f32_e32 v26, v26, v27
	s_cselect_b64 s[4:5], -1, 0
	v_exp_f32_e32 v26, v26
	s_and_b64 vcc, s[4:5], exec
	s_waitcnt lgkmcnt(0)
	s_barrier
	ds_read_b128 v[0:3], v47
	ds_read_b128 v[4:7], v47 offset:64
	ds_read_b128 v[8:11], v48 offset:33792
	ds_read_b128 v[12:15], v48 offset:33856
	ds_read_b128 v[16:19], v49 offset:33792
	ds_read_b128 v[20:23], v49 offset:33856
	ds_read_b128 v[52:55], v47 offset:128
	ds_read_b128 v[56:59], v47 offset:192
	ds_read_b128 v[60:63], v48 offset:33920
	ds_read_b128 v[64:67], v48 offset:33984
	ds_read_b128 v[68:71], v49 offset:33920
	ds_read_b128 v[72:75], v49 offset:33984
	ds_read_b128 v[76:79], v47 offset:256
	ds_read_b128 v[80:83], v47 offset:320
	ds_read_b128 v[84:87], v48 offset:34048
	ds_read_b128 v[88:91], v48 offset:34112
	ds_read_b128 v[92:95], v49 offset:34048
	ds_read_b128 v[96:99], v49 offset:34112
	ds_read_b128 v[100:103], v47 offset:384
	ds_read_b128 v[104:107], v47 offset:448
	ds_read_b128 v[108:111], v48 offset:34176
	ds_read_b128 v[112:115], v48 offset:34240
	ds_read_b128 v[116:119], v49 offset:34176
	ds_read_b128 v[120:123], v49 offset:34240
	s_add_i32 s5, s10, s33
	s_cmpk_lt_i32 s5, 0x800
	s_cselect_b32 s5, s5, s36
	s_waitcnt lgkmcnt(14)
	v_mfma_f32_16x16x32_bf16 v[8:11], v[8:11], v[0:3], 0
	s_ashr_i32 s4, s5, 9
	s_ashr_i32 s37, s36, 31
	s_lshl_b32 s11, s5, 6
	v_mfma_f32_16x16x32_bf16 v[0:3], v[16:19], v[0:3], 0
	s_lshl_b32 s12, s5, 2
	s_ashr_i32 s5, s4, 31
	v_ldexp_f32 v26, v26, s6
	s_lshl_b64 s[6:7], s[36:37], 13
	s_mov_b32 s36, s10
	s_and_b32 s10, s11, 0x1fc0
	s_lshl_b64 s[4:5], s[4:5], 13
	s_or_b32 s4, s4, s10
	v_mov_b64_e32 v[24:25], s[62:63]
	v_mfma_f32_16x16x32_bf16 v[128:131], v[20:23], v[4:7], v[0:3]
	s_and_b32 s24, s12, 0x600
	v_sub_f32_e32 v16, 1.0, v26
	v_log_f32_e32 v134, v16
	v_lshl_add_u64 v[0:1], s[4:5], 0, v[32:33]
	v_mad_u64_u32 v[2:3], s[4:5], v0, s1, v[24:25]
	v_mad_i32_i24 v3, v1, s1, v3
	v_lshl_add_u64 v[0:1], v[2:3], 0, s[24:25]
	v_mfma_f32_16x16x32_bf16 v[124:127], v[12:15], v[4:7], v[8:11]
	v_mul_f32_e32 v135, v134, v39
	v_mul_f32_e32 v136, v134, v40
	v_mul_f32_e32 v137, v134, v41
	v_lshl_add_u64 v[8:9], v[0:1], 0, v[34:35]
	v_add_co_u32_e64 v10, s[4:5], s27, v8
	global_load_dwordx4 v[176:179], v[8:9], off
	global_load_dwordx4 v[180:183], v[8:9], off offset:2048
	v_addc_co_u32_e64 v11, s[4:5], 0, v9, s[4:5]
	v_add_co_u32_e64 v12, s[4:5], s38, v8
	v_mfma_f32_16x16x32_bf16 v[60:63], v[60:63], v[52:55], v[124:127]
	s_nop 0
	v_addc_co_u32_e64 v13, s[4:5], 0, v9, s[4:5]
	v_add_co_u32_e64 v20, s[4:5], s39, v8
	s_waitcnt lgkmcnt(13)
	v_mfma_f32_16x16x32_bf16 v[52:55], v[68:71], v[52:55], v[128:131]
	v_addc_co_u32_e64 v21, s[4:5], 0, v9, s[4:5]
	global_load_dwordx4 v[184:187], v[10:11], off
	s_nop 0
	global_load_dwordx4 v[188:191], v[10:11], off offset:2048
	s_nop 0
	global_load_dwordx4 v[192:195], v[12:13], off
	s_nop 0
	global_load_dwordx4 v[196:199], v[12:13], off offset:2048
	s_nop 0
	global_load_dwordx4 v[200:203], v[20:21], off
	s_nop 0
	global_load_dwordx4 v[204:207], v[20:21], off offset:2048
	v_mfma_f32_16x16x32_bf16 v[60:63], v[64:67], v[56:59], v[60:63]
	v_mul_f32_e32 v138, v134, v42
	v_lshl_add_u64 v[132:133], v[36:37], 0, s[6:7]
	v_mul_f32_e32 v139, v134, v38
	s_waitcnt lgkmcnt(12)
	v_mfma_f32_16x16x32_bf16 v[52:55], v[72:75], v[56:59], v[52:55]
	v_mul_f32_e32 v140, v134, v43
	v_mul_f32_e32 v141, v134, v44
	v_mul_f32_e32 v142, v134, v45
	s_waitcnt lgkmcnt(9)
	v_mfma_f32_16x16x32_bf16 v[56:59], v[84:87], v[76:79], v[60:63]
	v_cmp_gt_f32_e64 s[4:5], s0, v135
	v_cmp_gt_f32_e64 s[6:7], s0, v136
	v_cmp_gt_f32_e64 s[10:11], s0, v137
	s_waitcnt lgkmcnt(7)
	v_mfma_f32_16x16x32_bf16 v[52:55], v[92:95], v[76:79], v[52:55]
	v_cmp_gt_f32_e64 s[12:13], s0, v138
	v_cndmask_b32_e64 v135, 0, v50, s[4:5]
	v_cndmask_b32_e64 v136, 0, v50, s[6:7]
	v_mfma_f32_16x16x32_bf16 v[56:59], v[88:91], v[80:83], v[56:59]
	v_cndmask_b32_e64 v137, 0, v50, s[10:11]
	v_cndmask_b32_e64 v138, 0, v50, s[12:13]
	v_cmp_gt_f32_e64 s[14:15], s0, v139
	s_waitcnt lgkmcnt(6)
	v_mfma_f32_16x16x32_bf16 v[52:55], v[96:99], v[80:83], v[52:55]
	v_cmp_gt_f32_e64 s[16:17], s0, v140
	v_cmp_gt_f32_e64 s[18:19], s0, v141
	v_cmp_gt_f32_e64 s[20:21], s0, v142
	s_waitcnt lgkmcnt(3)
	v_mfma_f32_16x16x32_bf16 v[56:59], v[108:111], v[100:103], v[56:59]
	v_cndmask_b32_e64 v139, 0, v50, s[14:15]
	v_cndmask_b32_e64 v140, 0, v50, s[16:17]
	v_cndmask_b32_e64 v124, 0, v50, s[18:19]
	s_waitcnt lgkmcnt(1)
	v_mfma_f32_16x16x32_bf16 v[52:55], v[116:119], v[100:103], v[52:55]
	v_cndmask_b32_e64 v125, 0, v50, s[20:21]
	v_fmac_f32_e32 v135, v134, v39
	v_fmac_f32_e32 v136, v134, v40
	v_fmac_f32_e32 v137, v134, v41
	v_fmac_f32_e32 v138, v134, v42
	v_fmac_f32_e32 v139, v134, v38
	v_fmac_f32_e32 v140, v134, v43
	v_fmac_f32_e32 v124, v134, v44
	v_fmac_f32_e32 v125, v134, v45
	v_exp_f32_e32 v60, v135
	v_exp_f32_e32 v61, v136
	v_exp_f32_e32 v62, v137
	v_exp_f32_e32 v63, v138
	v_exp_f32_e32 v72, v139
	v_exp_f32_e32 v73, v140
	v_exp_f32_e32 v74, v124
	v_exp_f32_e32 v75, v125
	v_mfma_f32_16x16x32_bf16 v[56:59], v[112:115], v[104:107], v[56:59]
	v_cndmask_b32_e64 v68, 0, v51, s[4:5]
	v_cndmask_b32_e64 v69, 0, v51, s[6:7]
	v_cndmask_b32_e64 v64, 0, v51, s[10:11]
	s_waitcnt lgkmcnt(0)
	v_mfma_f32_16x16x32_bf16 v[52:55], v[120:123], v[104:107], v[52:55]
	v_cndmask_b32_e64 v65, 0, v51, s[12:13]
	v_cndmask_b32_e64 v66, 0, v51, s[14:15]
	v_cndmask_b32_e64 v67, 0, v51, s[16:17]
	v_cndmask_b32_e64 v70, 0, v51, s[18:19]
	v_cndmask_b32_e64 v71, 0, v51, s[20:21]
	v_ldexp_f32 v60, v60, v68
	v_ldexp_f32 v61, v61, v69
	v_ldexp_f32 v62, v62, v64
	v_ldexp_f32 v63, v63, v65
	v_ldexp_f32 v64, v72, v66
	v_ldexp_f32 v65, v73, v67
	v_ldexp_f32 v66, v74, v70
	v_ldexp_f32 v67, v75, v71
	v_pk_mul_f32 v[56:57], v[60:61], v[56:57]
	v_pk_mul_f32 v[58:59], v[62:63], v[58:59]
	v_pk_mul_f32 v[52:53], v[64:65], v[52:53]
	v_pk_mul_f32 v[54:55], v[66:67], v[54:55]
	v_cvt_pk_bf16_f32 v56, v56, v57
	v_cvt_pk_bf16_f32 v57, v58, v59
	v_cvt_pk_bf16_f32 v52, v52, v53
	v_cvt_pk_bf16_f32 v53, v54, v55
	global_store_dwordx2 v[132:133], v[56:57], off
	global_store_dwordx2 v[132:133], v[52:53], off offset:32
	s_barrier
	s_cbranch_vccnz .LBB0_350
